# DF early half: stop-flag address computed before the step rendezvous (4 instrs off the post-barrier path, no-op add dropped); on top of version 123
# speedup vs baseline: 1.0011x; 1.0011x over previous
.LBB0_433:
	s_add_i32 s23, s22, 8
	s_and_b32 s24, s23, 8
	s_add_i32 s24, s24, 0x241c0
	v_mov_b32_e32 v0, s24
	s_andn2_b64 vcc, exec, s[8:9]
	s_cbranch_vccnz .LBB0_435
	s_waitcnt vmcnt(8) lgkmcnt(0)
	s_barrier
.LBB0_435:
	ds_read_b64 v[2:3], v0
	s_cmp_lt_i32 s15, 3
	s_cbranch_scc1 .LBB0_437
	s_and_b32 s11, s13, 0xc000
	s_cmp_gt_i32 s14, 1
	s_cselect_b32 s8, -2, 3
	s_add_i32 s8, s8, s14
	s_add_i32 s80, s10, -4
	s_lshl_b32 s24, s8, 14
	s_lshl_b64 s[8:9], s[80:81], 14
	v_lshl_add_u64 v[4:5], v[180:181], 0, s[8:9]
	s_add_i32 s11, s76, s11
	s_mov_b32 s25, m0
	s_mov_b32 m0, s11
	s_nop 0
	global_load_lds_dwordx4 v[4:5], off
	s_mov_b32 m0, s25
	v_lshl_add_u64 v[4:5], v[4:5], 0, s[88:89]
	s_addk_i32 s11, 0x2000
	s_mov_b32 s25, m0
	s_mov_b32 m0, s11
	s_nop 0
	global_load_lds_dwordx4 v[4:5], off
	s_mov_b32 m0, s25
	v_lshl_add_u64 v[4:5], v[182:183], 0, s[8:9]
	s_add_i32 s8, s31, s24
	s_mov_b32 s9, m0
	s_mov_b32 m0, s8
	s_nop 0
	global_load_lds_dwordx4 v[4:5], off
	s_mov_b32 m0, s9
	v_lshl_add_u64 v[4:5], v[4:5], 0, s[88:89]
	s_addk_i32 s8, 0x2000
	s_mov_b32 s9, m0
	s_mov_b32 m0, s8
	s_nop 0
	global_load_lds_dwordx4 v[4:5], off
	s_mov_b32 m0, s9
